# P2d/GEMM overlap (Option X) class keyed on workgroup id bit 3 (within each XCD) instead of bit 0 (XCD parity)
# baseline (speedup 1.0000x reference)
; __global__ void __launch_bounds__(512, 2) hybrid_fwd(Args args) {
;     ...
;     DUP_BEGIN(4) if (IN(4)) { for (int u = F.bid; u < 2048; u += F.G) p2d_unit(F, u, HY, UT, Kb, args.in[5], args.in[6]); }
;     DUP_END(4)
;     SEAM(4);
;     DUP_BEGIN(5) if (IN(5)) {
;         pg8::StaticOrder S; S.init(MTOK, DM, F.G, F.bid);
;         { pg8::Gemm g{XB, WIN + (size_t)3072 * DM, MTOK, DM, DM}; EpiGate E{M1, SS0}; pg8::gemm_phase<EpiGate, pg8::StaticOrder, true, true>(F.lds, g, S, E); }
;         { pg8::Gemm g{Qb, WBA, MTOK, DM, 512}; EpiMix<0> E{M1, nullptr}; pg8::gemm_phase<EpiMix<0>, pg8::StaticOrder, true, true>(F.lds, g, S, E); }
;         { pg8::Gemm g{XB, WIN + (size_t)4096 * DM, MTOK, DM, DM}; EpiGate E{M2, SS0}; pg8::gemm_phase<EpiGate, pg8::StaticOrder, true, true>(F.lds, g, S, E); }
;         { pg8::Gemm g{Kb, WBH, MTOK, DM, 512}; EpiMix<1> E{M1, M2}; pg8::gemm_phase<EpiMix<1>, pg8::StaticOrder, true, true>(F.lds, g, S, E); }
.LBB0_1164:
	v_cmp_ne_u32_e32 vcc, 0, v255
	s_cbranch_vccnz .Lx_h1_done
	s_bitcmp1_b32 s33, 3
	s_cbranch_scc1 .Lx_h1_odd
	v_mov_b32_e32 v255, 1
	s_mov_b64 s[0:1], -1
	s_branch .LBB0_1229
